# attention: per-segment priority, s_setprio 1 at the head of each QK block and 0 after the last PV MFMA
# speedup vs baseline: 1.0091x; 1.0091x over previous
; #define LAS __attribute__((address_space(3)))
; __device__ __forceinline__ void finishSM(f32x16& p0, f32x16& p1, float alpha, float& l_reg, bf16x8& pa0, bf16x8& pa1, bf16x8& pa2, bf16x8& pa3) {
; #pragma unroll
;     for (int r = 0; r < 16; ++r) p1[r] = __builtin_amdgcn_exp2f(p1[r]);
;     float ps = 0;
; #pragma unroll
;     for (int r = 0; r < 16; ++r) ps += p0[r];
; #pragma unroll
;     for (int r = 0; r < 16; ++r) ps += p1[r];
;     { auto rr = __builtin_amdgcn_permlane32_swap(__float_as_uint(ps), __float_as_uint(ps), false, false);
;       ps = __uint_as_float(rr[0]) + __uint_as_float(rr[1]); }
;     l_reg = l_reg * alpha + ps;
;     ...
;     PK4(p0, 0, pa0); PK4(p0, 8, pa1); PK4(p1, 0, pa2); PK4(p1, 8, pa3);
;     ...
; }
; template <int KB>
; __device__ __forceinline__ void qkt(f32x16& p0, f32x16& p1, const LAS char* lds, int r32, int hi, const bf16x8* qr, const LAS char* qrb) {
;     p0 = f32x16{}; p1 = f32x16{};
;     { const LAS char* kbp = lds + OFF_K + KB * SHM_K + KSWZ(r32, hi * 16);
; #pragma unroll
;     for (int d0 = 0; d0 < 8; ++d0) { const LAS char* a = kbp + d0 * 32;
;         const bf16x8 b0 = *reinterpret_cast<const LAS bf16x8*>(a);
;         const bf16x8 b1 = *reinterpret_cast<const LAS bf16x8*>(a + 32 * 272);
;         p0 = __builtin_amdgcn_mfma_f32_32x32x16_bf16(b0, qr[d0], p0, 0, 0, 0);
;         p1 = __builtin_amdgcn_mfma_f32_32x32x16_bf16(b1, qr[d0], p1, 0, 0, 0); } }
;     { const LAS char* rb = lds + OFF_R + KB * SHM_R + RSWZ(r32, hi * 16);
; #pragma unroll
;     for (int d0 = 0; d0 < 4; ++d0) { const LAS char* a = rb + d0 * 32;
;         const bf16x8 b0 = *reinterpret_cast<const LAS bf16x8*>(a);
;         const bf16x8 b1 = *reinterpret_cast<const LAS bf16x8*>(a + 32 * 144);
;         const bf16x8 qv = *reinterpret_cast<const LAS bf16x8*>(qrb + d0 * 1024);
;         p0 = __builtin_amdgcn_mfma_f32_32x32x16_bf16(b0, qv, p0, 0, 0, 0);
;         p1 = __builtin_amdgcn_mfma_f32_32x32x16_bf16(b1, qv, p1, 0, 0, 0); } }
; }
.LBB0_506:
	s_setprio 1
	ds_read_b128 v[210:213], v176
	ds_read_b128 v[214:217], v176 offset:8704
	ds_read_b128 v[218:221], v176 offset:32
	ds_read_b128 v[222:225], v176 offset:8736
	ds_read_b128 v[226:229], v176 offset:64
	ds_read_b128 v[230:233], v176 offset:8768
	ds_read_b128 v[234:237], v176 offset:96
	ds_read_b128 v[238:241], v176 offset:8800
	ds_read_b128 v[242:245], v176 offset:128
	ds_read_b128 v[246:249], v176 offset:8832
	v_exp_f32_e32 v0, v164
	v_exp_f32_e32 v164, v165
	v_exp_f32_e32 v162, v162
	v_exp_f32_e32 v163, v163
	s_waitcnt lgkmcnt(6)
	v_mfma_f32_32x32x16_bf16 v[82:97], v[210:213], v[126:129], 0
	ds_read_b128 v[210:213], v176 offset:160
	v_exp_f32_e32 v160, v160
	v_exp_f32_e32 v165, v157
	v_mfma_f32_32x32x16_bf16 v[66:81], v[214:217], v[126:129], 0
	ds_read_b128 v[214:217], v176 offset:8864
	v_exp_f32_e32 v190, v154
	v_mfma_f32_32x32x16_bf16 v[82:97], v[218:221], v[122:125], v[82:97]
	ds_read_b128 v[218:221], v176 offset:192
	v_exp_f32_e32 v191, v155
	v_exp_f32_e32 v130, v161
	v_mfma_f32_32x32x16_bf16 v[66:81], v[222:225], v[122:125], v[66:81]
	ds_read_b128 v[222:225], v176 offset:8896
	v_exp_f32_e32 v131, v158
	v_exp_f32_e32 v132, v159
	s_waitcnt lgkmcnt(6)
	v_mfma_f32_32x32x16_bf16 v[82:97], v[226:229], v[118:121], v[82:97]
	ds_read_b128 v[226:229], v176 offset:224
	v_exp_f32_e32 v133, v156
	v_exp_f32_e32 v148, v150
	v_mfma_f32_32x32x16_bf16 v[66:81], v[230:233], v[118:121], v[66:81]
	ds_read_b128 v[230:233], v176 offset:8928
	v_add_f32_e32 v150, 0, v205
	v_add_f32_e32 v150, v207, v150
	v_mfma_f32_32x32x16_bf16 v[82:97], v[234:237], v[114:117], v[82:97]
	ds_read_b128 v[234:237], v178
	v_add_f32_e32 v150, v203, v150
	v_exp_f32_e32 v146, v152
	v_exp_f32_e32 v147, v153
	v_mfma_f32_32x32x16_bf16 v[66:81], v[238:241], v[114:117], v[66:81]
	ds_read_b128 v[238:241], v177
	v_exp_f32_e32 v149, v151
	s_waitcnt lgkmcnt(6)
	v_mfma_f32_32x32x16_bf16 v[82:97], v[242:245], v[110:113], v[82:97]
	ds_read_b128 v[242:245], v177 offset:4608
	v_add_f32_e32 v142, v206, v150
	v_add_f32_e32 v142, v202, v142
	v_add_f32_e32 v142, v204, v142
	v_add_f32_e32 v142, v200, v142
	v_mfma_f32_32x32x16_bf16 v[66:81], v[246:249], v[110:113], v[66:81]
	ds_read_b128 v[246:249], v178 offset:1024
	v_add_f32_e32 v142, v201, v142
	v_add_f32_e32 v142, v197, v142
	v_add_f32_e32 v142, v199, v142
	v_mfma_f32_32x32x16_bf16 v[82:97], v[210:213], v[106:109], v[82:97]
	ds_read_b128 v[210:213], v177 offset:32
	v_add_f32_e32 v142, v196, v142
	v_add_f32_e32 v142, v198, v142
	v_add_f32_e32 v142, v193, v142
	v_add_f32_e32 v142, v195, v142
	v_mfma_f32_32x32x16_bf16 v[66:81], v[214:217], v[106:109], v[66:81]
	ds_read_b128 v[214:217], v177 offset:4640
	v_add_f32_e32 v142, v192, v142
	v_add_f32_e32 v142, v194, v142
	v_add_f32_e32 v142, v0, v142
	s_waitcnt lgkmcnt(6)
	v_mfma_f32_32x32x16_bf16 v[82:97], v[218:221], v[102:105], v[82:97]
	ds_read_b128 v[218:221], v178 offset:2048
	v_add_f32_e32 v142, v164, v142
	v_add_f32_e32 v142, v162, v142
	v_add_f32_e32 v142, v163, v142
	v_add_f32_e32 v142, v160, v142
	v_mfma_f32_32x32x16_bf16 v[66:81], v[222:225], v[102:105], v[66:81]
	ds_read_b128 v[222:225], v177 offset:64
	v_add_f32_e32 v142, v130, v142
	v_add_f32_e32 v142, v131, v142
	v_add_f32_e32 v142, v132, v142
	v_mfma_f32_32x32x16_bf16 v[82:97], v[226:229], v[98:101], v[82:97]
	ds_read_b128 v[226:229], v177 offset:4672
	v_add_f32_e32 v134, v133, v142
	v_add_f32_e32 v134, v165, v134
	v_add_f32_e32 v134, v190, v134
	v_add_f32_e32 v134, v191, v134
	v_mfma_f32_32x32x16_bf16 v[66:81], v[230:233], v[98:101], v[66:81]
	ds_read_b128 v[230:233], v178 offset:3072
	v_add_f32_e32 v134, v146, v134
	v_add_f32_e32 v134, v147, v134
	v_add_f32_e32 v134, v148, v134
	s_waitcnt lgkmcnt(5)
	v_mfma_f32_32x32x16_bf16 v[82:97], v[238:241], v[234:237], v[82:97]
	ds_read_b128 v[238:241], v177 offset:96
	v_add_f32_e32 v186, v149, v134
	v_mov_b32_e32 v187, v186
	s_nop 1
	v_permlane32_swap_b32_e32 v186, v187
	v_mfma_f32_32x32x16_bf16 v[66:81], v[242:245], v[234:237], v[66:81]
	ds_read_b128 v[242:245], v177 offset:4704
	v_cvt_pk_bf16_f32 v150, v205, v207
	v_cvt_pk_bf16_f32 v151, v203, v206
	v_cvt_pk_bf16_f32 v152, v202, v204
	v_cvt_pk_bf16_f32 v153, v200, v201
	v_mfma_f32_32x32x16_bf16 v[82:97], v[210:213], v[246:249], v[82:97]
	v_cvt_pk_bf16_f32 v154, v197, v199
	v_cvt_pk_bf16_f32 v155, v196, v198
	v_cvt_pk_bf16_f32 v156, v193, v195
	s_waitcnt lgkmcnt(3)
	v_mfma_f32_32x32x16_bf16 v[66:81], v[214:217], v[246:249], v[66:81]
	v_cvt_pk_bf16_f32 v157, v192, v194
	v_cvt_pk_bf16_f32 v158, v0, v164
	v_cvt_pk_bf16_f32 v159, v162, v163
	v_cvt_pk_bf16_f32 v160, v160, v130
	v_mfma_f32_32x32x16_bf16 v[82:97], v[222:225], v[218:221], v[82:97]
	v_cvt_pk_bf16_f32 v161, v131, v132
	v_cvt_pk_bf16_f32 v162, v133, v165
	v_cvt_pk_bf16_f32 v163, v190, v191
	v_mfma_f32_32x32x16_bf16 v[66:81], v[226:229], v[218:221], v[66:81]
	v_cvt_pk_bf16_f32 v164, v146, v147
	v_cvt_pk_bf16_f32 v165, v148, v149
	v_permlane32_swap_b32_e32 v150, v152
	v_permlane32_swap_b32_e32 v151, v153
	s_waitcnt lgkmcnt(0)
	v_mfma_f32_32x32x16_bf16 v[82:97], v[238:241], v[230:233], v[82:97]
	v_permlane32_swap_b32_e32 v154, v156
	v_permlane32_swap_b32_e32 v155, v157
	v_permlane32_swap_b32_e32 v158, v160
	v_mfma_f32_32x32x16_bf16 v[66:81], v[242:245], v[230:233], v[66:81]
	v_permlane32_swap_b32_e32 v159, v161
	v_permlane32_swap_b32_e32 v162, v164
	v_permlane32_swap_b32_e32 v163, v165
	v_add_u32_e32 v0, 0x20000, v254
	global_load_dwordx4 v[130:133], v254, s[98:99] offset:256
	global_load_dwordx4 v[138:141], v254, s[98:99]
	global_load_dwordx4 v[134:137], v0, s[98:99] offset:256
	global_load_dwordx4 v[142:145], v0, s[98:99]
	v_lshlrev_b32_e32 v0, 4, v166
	global_load_dwordx4 v[146:149], v0, s[100:101]
	s_add_u32 s98, s98, 0x40000
	s_addc_u32 s99, s99, 0
	s_add_u32 s100, s100, 0x2000
	s_addc_u32 s101, s101, 0
	s_add_i32 s5, s96, 0xffffff9f
	s_cmp_le_i32 s5, s85
	s_cbranch_scc0 .Lattn_slow1
; __device__ __forceinline__ void partialSM(f32x16& p0, f32x16& p1, float& m_reg, float& mn, float& alpha) {
;     float pmax = p0[0];
; #pragma unroll
;     for (int r = 1; r < 16; ++r) pmax = fmaxf(pmax, p0[r]);
; #pragma unroll
;     for (int r = 0; r < 16; ++r) pmax = fmaxf(pmax, p1[r]);
;     { auto rr = __builtin_amdgcn_permlane32_swap(__float_as_uint(pmax), __float_as_uint(pmax), false, false);
;       pmax = fmaxf(__uint_as_float(rr[0]), __uint_as_float(rr[1])); }
;     constexpr float C2 = 1.4426950408889634f * ATT_SCALE;
;     if (__builtin_expect(__all((pmax - m_reg) * ATT_SCALE <= THR), 1)) { mn = m_reg; alpha = 1.f; }
;     else { mn = fmaxf(m_reg, pmax); alpha = __builtin_amdgcn_exp2f((m_reg - mn) * C2); m_reg = mn; }
;     const float mnL = -mn * C2;
; #pragma unroll
;     for (int r = 0; r < 16; ++r) p0[r] = fmaf(p0[r], C2, mnL);
; #pragma unroll
;     for (int r = 0; r < 16; ++r) p1[r] = fmaf(p1[r], C2, mnL);
; #pragma unroll
;     for (int r = 0; r < 16; ++r) p0[r] = __builtin_amdgcn_exp2f(p0[r]);
; }
; template <int VB>
; __device__ __forceinline__ void pv_tile(f32x16* o, int vb0, bf16x8 pa0, bf16x8 pa1, bf16x8 pa2, bf16x8 pa3) {
;     ...
;     PV_D0(0); PV_D0(1); PV_D0(2); PV_D0(3);
;     ...
; }
	s_lshl_b32 s4, s74, 14
	v_add_u32_e32 v242, s4, v169
	ds_read_b64_tr_b16 v[222:223], v242 offset:0
	ds_read_b64_tr_b16 v[224:225], v242 offset:0x800
	ds_read_b64_tr_b16 v[226:227], v242 offset:0x1000
	ds_read_b64_tr_b16 v[228:229], v242 offset:0x1800
	ds_read_b64_tr_b16 v[230:231], v242 offset:0x2000
	ds_read_b64_tr_b16 v[232:233], v242 offset:0x2800
	ds_read_b64_tr_b16 v[234:235], v242 offset:0x3000
	ds_read_b64_tr_b16 v[236:237], v242 offset:0x3800
	v_max_f32_e32 v0, v82, v83
	v_max3_f32 v0, v0, v84, v85
	v_max3_f32 v0, v0, v86, v87
	v_max3_f32 v0, v0, v88, v89
	s_waitcnt lgkmcnt(0)
	s_nop 0
	v_mfma_f32_32x32x16_bf16 v[50:65], v[150:153], v[222:225], v[50:65]
	ds_read_b64_tr_b16 v[222:223], v242 offset:0x200
	ds_read_b64_tr_b16 v[224:225], v242 offset:0xa00
	v_max3_f32 v0, v0, v90, v91
	v_max3_f32 v0, v0, v92, v93
	v_max3_f32 v0, v0, v94, v95
	v_max3_f32 v0, v0, v96, v97
	v_max3_f32 v0, v0, v66, v67
	v_max3_f32 v0, v0, v68, v69
	v_mfma_f32_32x32x16_bf16 v[50:65], v[154:157], v[226:229], v[50:65]
	ds_read_b64_tr_b16 v[226:227], v242 offset:0x1200
	ds_read_b64_tr_b16 v[228:229], v242 offset:0x1a00
	v_max3_f32 v0, v0, v70, v71
	v_max3_f32 v0, v0, v72, v73
	v_max3_f32 v0, v0, v74, v75
	v_max3_f32 v0, v0, v76, v77
	v_max3_f32 v0, v0, v78, v79
	v_max3_f32 v0, v0, v80, v81
	v_mfma_f32_32x32x16_bf16 v[50:65], v[158:161], v[230:233], v[50:65]
	ds_read_b64_tr_b16 v[230:231], v242 offset:0x2200
	ds_read_b64_tr_b16 v[232:233], v242 offset:0x2a00
	ds_read_b64_tr_b16 v[238:239], v242 offset:0x3200
	ds_read_b64_tr_b16 v[240:241], v242 offset:0x3a00
	v_mov_b32_e32 v243, v0
	s_nop 1
	v_permlane32_swap_b32_e32 v0, v243
	v_max_f32_e32 v0, v0, v243
	v_sub_f32_e32 v243, v0, v185
	v_max_f32_e32 v0, v185, v0
	v_sub_f32_e32 v244, v185, v0
	s_waitcnt lgkmcnt(0)
	v_mfma_f32_32x32x16_bf16 v[50:65], v[162:165], v[234:237], v[50:65]
	v_mul_f32_e32 v244, 0x3dd53b94, v244
	v_mul_f32_e32 v243, 0x3d93cd3a, v243
	v_exp_f32_e32 v244, v244
	v_cmp_ge_f32_e32 vcc, s73, v243
	s_cmp_eq_u64 vcc, exec
	s_cselect_b64 s[10:11], -1, 0
	v_mfma_f32_32x32x16_bf16 v[34:49], v[150:153], v[222:225], v[34:49]
	ds_read_b64_tr_b16 v[222:223], v242 offset:0x400
	ds_read_b64_tr_b16 v[224:225], v242 offset:0xc00
	v_cndmask_b32_e64 v189, v244, 1.0, s[10:11]
	v_cndmask_b32_e64 v0, v0, v185, s[10:11]
	v_mul_f32_e32 v185, 0xbdd53b94, v0
	v_fmamk_f32 v82, v82, 0x3dd53b94, v185
	v_fmamk_f32 v83, v83, 0x3dd53b94, v185
	v_fmamk_f32 v84, v84, 0x3dd53b94, v185
	v_mfma_f32_32x32x16_bf16 v[34:49], v[154:157], v[226:229], v[34:49]
	ds_read_b64_tr_b16 v[226:227], v242 offset:0x1400
	ds_read_b64_tr_b16 v[228:229], v242 offset:0x1c00
	v_fmamk_f32 v85, v85, 0x3dd53b94, v185
	v_fmamk_f32 v86, v86, 0x3dd53b94, v185
	v_fmamk_f32 v87, v87, 0x3dd53b94, v185
	v_fmamk_f32 v88, v88, 0x3dd53b94, v185
	v_fmamk_f32 v89, v89, 0x3dd53b94, v185
	v_fmamk_f32 v90, v90, 0x3dd53b94, v185
	v_mfma_f32_32x32x16_bf16 v[34:49], v[158:161], v[230:233], v[34:49]
	ds_read_b64_tr_b16 v[230:231], v242 offset:0x2400
	ds_read_b64_tr_b16 v[232:233], v242 offset:0x2c00
	ds_read_b64_tr_b16 v[234:235], v242 offset:0x3400
	ds_read_b64_tr_b16 v[236:237], v242 offset:0x3c00
	v_fmamk_f32 v91, v91, 0x3dd53b94, v185
	v_fmamk_f32 v92, v92, 0x3dd53b94, v185
	v_fmamk_f32 v93, v93, 0x3dd53b94, v185
	v_fmamk_f32 v94, v94, 0x3dd53b94, v185
	v_fmamk_f32 v95, v95, 0x3dd53b94, v185
	v_fmamk_f32 v96, v96, 0x3dd53b94, v185
	v_fmamk_f32 v97, v97, 0x3dd53b94, v185
	s_waitcnt lgkmcnt(0)
	v_mfma_f32_32x32x16_bf16 v[34:49], v[162:165], v[238:241], v[34:49]
	v_fmamk_f32 v190, v67, 0x3dd53b94, v185
	v_fmamk_f32 v191, v68, 0x3dd53b94, v185
	v_fmamk_f32 v188, v66, 0x3dd53b94, v185
	v_fmamk_f32 v192, v69, 0x3dd53b94, v185
	v_fmamk_f32 v193, v70, 0x3dd53b94, v185
	v_fmamk_f32 v194, v71, 0x3dd53b94, v185
	v_mfma_f32_32x32x16_bf16 v[18:33], v[150:153], v[222:225], v[18:33]
	ds_read_b64_tr_b16 v[222:223], v242 offset:0x600
	ds_read_b64_tr_b16 v[224:225], v242 offset:0xe00
	v_fmamk_f32 v195, v72, 0x3dd53b94, v185
	v_fmamk_f32 v196, v73, 0x3dd53b94, v185
	v_fmamk_f32 v197, v74, 0x3dd53b94, v185
	v_fmamk_f32 v198, v75, 0x3dd53b94, v185
	v_fmamk_f32 v199, v76, 0x3dd53b94, v185
	v_fmamk_f32 v200, v77, 0x3dd53b94, v185
	v_mfma_f32_32x32x16_bf16 v[18:33], v[154:157], v[226:229], v[18:33]
	ds_read_b64_tr_b16 v[226:227], v242 offset:0x1600
	ds_read_b64_tr_b16 v[228:229], v242 offset:0x1e00
	v_fmamk_f32 v201, v78, 0x3dd53b94, v185
	v_fmamk_f32 v202, v79, 0x3dd53b94, v185
	v_fmamk_f32 v203, v80, 0x3dd53b94, v185
	v_fmac_f32_e32 v185, 0x3dd53b94, v81
	v_exp_f32_e32 v204, v82
	v_mfma_f32_32x32x16_bf16 v[18:33], v[158:161], v[230:233], v[18:33]
	ds_read_b64_tr_b16 v[230:231], v242 offset:0x2600
	ds_read_b64_tr_b16 v[232:233], v242 offset:0x2e00
	ds_read_b64_tr_b16 v[238:239], v242 offset:0x3600
	ds_read_b64_tr_b16 v[240:241], v242 offset:0x3e00
	v_exp_f32_e32 v205, v83
	v_exp_f32_e32 v206, v84
	v_exp_f32_e32 v207, v85
	s_waitcnt lgkmcnt(0)
	v_mfma_f32_32x32x16_bf16 v[18:33], v[162:165], v[234:237], v[18:33]
	v_exp_f32_e32 v209, v86
	v_exp_f32_e32 v210, v87
	v_exp_f32_e32 v211, v88
	v_mfma_f32_32x32x16_bf16 v[2:17], v[150:153], v[222:225], v[2:17]
	v_exp_f32_e32 v212, v89
	v_exp_f32_e32 v213, v90
	v_exp_f32_e32 v214, v91
	v_mfma_f32_32x32x16_bf16 v[2:17], v[154:157], v[226:229], v[2:17]
	v_exp_f32_e32 v215, v92
	v_exp_f32_e32 v216, v93
	v_exp_f32_e32 v217, v94
	v_mfma_f32_32x32x16_bf16 v[2:17], v[158:161], v[230:233], v[2:17]
	v_exp_f32_e32 v218, v95
	v_exp_f32_e32 v219, v96
	v_exp_f32_e32 v220, v97
	v_mfma_f32_32x32x16_bf16 v[2:17], v[162:165], v[238:241], v[2:17]
	s_setprio 0
	s_waitcnt vmcnt(3)
	ds_write_b128 v250, v[138:141] offset:49152
	s_waitcnt vmcnt(1)
	ds_write_b128 v250, v[142:145] offset:57856
	s_waitcnt vmcnt(0)
	v_add_u32_e32 v150, s76, v251
	ds_write_b128 v150, v[146:149]
	s_addk_i32 s4, 0xc000
	s_cmp_lg_u32 s74, 0
	s_cselect_b32 s4, s4, 0x8000
	v_add_u32_e32 v151, s4, v252
	v_add_u32_e32 v152, s4, v253
	v_cmp_gt_f32_e32 vcc, 1.0, v189
	ds_write_b128 v151, v[130:133]
	ds_write_b128 v152, v[134:137]
	s_cbranch_vccz .Lattn_f1_norsc
	s_and_saveexec_b64 s[4:5], s[8:9]
	ds_write_b32 v180, v189 offset:128
	s_or_b64 exec, exec, s[4:5]
	s_waitcnt lgkmcnt(0)
	ds_read_b128 v[150:153], v179 offset:224
	ds_read_b128 v[154:157], v179 offset:192
	ds_read_b128 v[158:161], v179 offset:160
	ds_read_b128 v[162:165], v179 offset:128
	s_waitcnt lgkmcnt(3)
	v_pk_mul_f32 v[64:65], v[64:65], v[152:153]
	s_waitcnt lgkmcnt(2)
	v_pk_mul_f32 v[60:61], v[60:61], v[156:157]
	s_waitcnt lgkmcnt(1)
	v_pk_mul_f32 v[56:57], v[56:57], v[160:161]
	s_waitcnt lgkmcnt(0)
	v_pk_mul_f32 v[52:53], v[52:53], v[164:165]
	v_pk_mul_f32 v[62:63], v[62:63], v[150:151]
	v_pk_mul_f32 v[58:59], v[58:59], v[154:155]
	v_pk_mul_f32 v[54:55], v[54:55], v[158:159]
	v_pk_mul_f32 v[50:51], v[50:51], v[162:163]
	v_pk_mul_f32 v[48:49], v[48:49], v[152:153]
	v_pk_mul_f32 v[44:45], v[44:45], v[156:157]
	v_pk_mul_f32 v[40:41], v[40:41], v[160:161]
	v_pk_mul_f32 v[36:37], v[36:37], v[164:165]
	v_pk_mul_f32 v[46:47], v[46:47], v[150:151]
	v_pk_mul_f32 v[42:43], v[42:43], v[154:155]
	v_pk_mul_f32 v[38:39], v[38:39], v[158:159]
	v_pk_mul_f32 v[34:35], v[34:35], v[162:163]
	v_pk_mul_f32 v[32:33], v[32:33], v[152:153]
	v_pk_mul_f32 v[28:29], v[28:29], v[156:157]
	v_pk_mul_f32 v[24:25], v[24:25], v[160:161]
	v_pk_mul_f32 v[20:21], v[20:21], v[164:165]
	v_pk_mul_f32 v[30:31], v[30:31], v[150:151]
	v_pk_mul_f32 v[26:27], v[26:27], v[154:155]
	v_pk_mul_f32 v[22:23], v[22:23], v[158:159]
	v_pk_mul_f32 v[18:19], v[18:19], v[162:163]
	v_pk_mul_f32 v[16:17], v[16:17], v[152:153]
	v_pk_mul_f32 v[12:13], v[12:13], v[156:157]
	v_pk_mul_f32 v[8:9], v[8:9], v[160:161]
	v_pk_mul_f32 v[4:5], v[4:5], v[164:165]
	v_pk_mul_f32 v[14:15], v[14:15], v[150:151]
	v_pk_mul_f32 v[10:11], v[10:11], v[154:155]
	v_pk_mul_f32 v[6:7], v[6:7], v[158:159]
	v_pk_mul_f32 v[2:3], v[2:3], v[162:163]

; #define LAS __attribute__((address_space(3)))
; __device__ __forceinline__ void finishSM(f32x16& p0, f32x16& p1, float alpha, float& l_reg, bf16x8& pa0, bf16x8& pa1, bf16x8& pa2, bf16x8& pa3) {
; #pragma unroll
;     for (int r = 0; r < 16; ++r) p1[r] = __builtin_amdgcn_exp2f(p1[r]);
;     float ps = 0;
; #pragma unroll
;     for (int r = 0; r < 16; ++r) ps += p0[r];
; #pragma unroll
;     for (int r = 0; r < 16; ++r) ps += p1[r];
;     { auto rr = __builtin_amdgcn_permlane32_swap(__float_as_uint(ps), __float_as_uint(ps), false, false);
;       ps = __uint_as_float(rr[0]) + __uint_as_float(rr[1]); }
;     l_reg = l_reg * alpha + ps;
;     ...
;     PK4(p0, 0, pa0); PK4(p0, 8, pa1); PK4(p1, 0, pa2); PK4(p1, 8, pa3);
;     ...
; }
; template <int KB>
; __device__ __forceinline__ void qkt(f32x16& p0, f32x16& p1, const LAS char* lds, int r32, int hi, const bf16x8* qr, const LAS char* qrb) {
;     p0 = f32x16{}; p1 = f32x16{};
;     { const LAS char* kbp = lds + OFF_K + KB * SHM_K + KSWZ(r32, hi * 16);
; #pragma unroll
;     for (int d0 = 0; d0 < 8; ++d0) { const LAS char* a = kbp + d0 * 32;
;         const bf16x8 b0 = *reinterpret_cast<const LAS bf16x8*>(a);
;         const bf16x8 b1 = *reinterpret_cast<const LAS bf16x8*>(a + 32 * 272);
;         p0 = __builtin_amdgcn_mfma_f32_32x32x16_bf16(b0, qr[d0], p0, 0, 0, 0);
;         p1 = __builtin_amdgcn_mfma_f32_32x32x16_bf16(b1, qr[d0], p1, 0, 0, 0); } }
;     { const LAS char* rb = lds + OFF_R + KB * SHM_R + RSWZ(r32, hi * 16);
; #pragma unroll
;     for (int d0 = 0; d0 < 4; ++d0) { const LAS char* a = rb + d0 * 32;
;         const bf16x8 b0 = *reinterpret_cast<const LAS bf16x8*>(a);
;         const bf16x8 b1 = *reinterpret_cast<const LAS bf16x8*>(a + 32 * 144);
;         const bf16x8 qv = *reinterpret_cast<const LAS bf16x8*>(qrb + d0 * 1024);
;         p0 = __builtin_amdgcn_mfma_f32_32x32x16_bf16(b0, qv, p0, 0, 0, 0);
;         p1 = __builtin_amdgcn_mfma_f32_32x32x16_bf16(b1, qv, p1, 0, 0, 0); } }
; }
.Lattn_s1b:
	s_setprio 1
	ds_read_b128 v[222:225], v172 offset:49152
	ds_read_b128 v[226:229], v172 offset:57856
	ds_read_b128 v[230:233], v172 offset:49184
	ds_read_b128 v[234:237], v172 offset:57888
	ds_read_b128 v[238:241], v172 offset:49216
	ds_read_b128 v[242:245], v172 offset:57920
	ds_read_b128 v[246:249], v172 offset:49248
	ds_read_b128 v[130:133], v172 offset:57952
	ds_read_b128 v[134:137], v172 offset:49280
	ds_read_b128 v[138:141], v172 offset:57984
	ds_read_b128 v[142:145], v172 offset:49312
	ds_read_b128 v[146:149], v172 offset:58016
	v_exp_f32_e32 v185, v185
	v_exp_f32_e32 v162, v193
	v_exp_f32_e32 v163, v194
	v_exp_f32_e32 v164, v195
	s_waitcnt lgkmcnt(8)
	v_mfma_f32_32x32x16_bf16 v[82:97], v[222:225], v[126:129], 0
	ds_read_b128 v[222:225], v172 offset:49344
	v_exp_f32_e32 v165, v196
	v_exp_f32_e32 v193, v199
	v_mfma_f32_32x32x16_bf16 v[66:81], v[226:229], v[126:129], 0
	ds_read_b128 v[226:229], v172 offset:58048
	v_exp_f32_e32 v194, v200
	v_mfma_f32_32x32x16_bf16 v[82:97], v[230:233], v[122:125], v[82:97]
	ds_read_b128 v[230:233], v172 offset:49376
	v_exp_f32_e32 v195, v201
	v_exp_f32_e32 v196, v202
	v_mfma_f32_32x32x16_bf16 v[66:81], v[234:237], v[122:125], v[66:81]
	ds_read_b128 v[234:237], v172 offset:58080
	v_add_f32_e32 v150, 0, v204
	v_add_f32_e32 v150, v205, v150
	v_add_f32_e32 v150, v206, v150
	s_waitcnt lgkmcnt(8)
	v_mfma_f32_32x32x16_bf16 v[82:97], v[238:241], v[118:121], v[82:97]
	ds_read_b128 v[238:241], v178
	v_add_f32_e32 v150, v207, v150
	v_add_f32_e32 v150, v209, v150
	v_add_f32_e32 v150, v210, v150
	v_add_f32_e32 v150, v211, v150
	v_mfma_f32_32x32x16_bf16 v[66:81], v[242:245], v[118:121], v[66:81]
	ds_read_b128 v[242:245], v173
	v_add_f32_e32 v150, v212, v150
	v_add_f32_e32 v150, v213, v150
	v_add_f32_e32 v150, v214, v150
	v_mfma_f32_32x32x16_bf16 v[82:97], v[246:249], v[114:117], v[82:97]
	ds_read_b128 v[246:249], v173 offset:4608
	v_add_f32_e32 v150, v215, v150
	v_add_f32_e32 v150, v216, v150
	v_exp_f32_e32 v158, v188
	v_mfma_f32_32x32x16_bf16 v[66:81], v[130:133], v[114:117], v[66:81]
	ds_read_b128 v[130:133], v178 offset:1024
	v_add_f32_e32 v150, v217, v150
	v_exp_f32_e32 v159, v190
	s_waitcnt lgkmcnt(8)
	v_mfma_f32_32x32x16_bf16 v[82:97], v[134:137], v[110:113], v[82:97]
	ds_read_b128 v[134:137], v173 offset:32
	v_add_f32_e32 v150, v218, v150
	v_exp_f32_e32 v160, v191
	v_add_f32_e32 v150, v219, v150
	v_mfma_f32_32x32x16_bf16 v[66:81], v[138:141], v[110:113], v[66:81]
	ds_read_b128 v[138:141], v173 offset:4640
	v_exp_f32_e32 v161, v192
	v_add_f32_e32 v150, v220, v150
	v_mfma_f32_32x32x16_bf16 v[82:97], v[142:145], v[106:109], v[82:97]
	ds_read_b128 v[142:145], v178 offset:2048
	v_add_f32_e32 v150, v158, v150
	v_add_f32_e32 v150, v159, v150
	v_add_f32_e32 v150, v160, v150
	v_add_f32_e32 v150, v161, v150
	v_mfma_f32_32x32x16_bf16 v[66:81], v[146:149], v[106:109], v[66:81]
	ds_read_b128 v[146:149], v173 offset:64
	v_exp_f32_e32 v188, v197
	v_add_f32_e32 v150, v162, v150
	s_waitcnt lgkmcnt(8)
	v_mfma_f32_32x32x16_bf16 v[82:97], v[222:225], v[102:105], v[82:97]
	ds_read_b128 v[222:225], v173 offset:4672
	v_exp_f32_e32 v192, v198
	v_add_f32_e32 v150, v163, v150
	v_add_f32_e32 v150, v164, v150
	v_mfma_f32_32x32x16_bf16 v[66:81], v[226:229], v[102:105], v[66:81]
	ds_read_b128 v[226:229], v178 offset:3072
	v_add_f32_e32 v150, v165, v150
	v_add_f32_e32 v150, v188, v150
	v_add_f32_e32 v150, v192, v150
	v_mfma_f32_32x32x16_bf16 v[82:97], v[230:233], v[98:101], v[82:97]
	ds_read_b128 v[230:233], v173 offset:96
	v_exp_f32_e32 v197, v203
	v_add_f32_e32 v150, v193, v150
	v_add_f32_e32 v150, v194, v150
	v_mfma_f32_32x32x16_bf16 v[66:81], v[234:237], v[98:101], v[66:81]
	ds_read_b128 v[234:237], v173 offset:4704
	v_add_f32_e32 v150, v195, v150
	v_add_f32_e32 v150, v196, v150
	v_add_f32_e32 v150, v197, v150
	s_waitcnt lgkmcnt(7)
	v_mfma_f32_32x32x16_bf16 v[82:97], v[242:245], v[238:241], v[82:97]
	v_add_f32_e32 v190, v185, v150
	v_mov_b32_e32 v191, v190
	v_cvt_pk_bf16_f32 v150, v204, v205
	v_cvt_pk_bf16_f32 v151, v206, v207
	v_mfma_f32_32x32x16_bf16 v[66:81], v[246:249], v[238:241], v[66:81]
	v_cvt_pk_bf16_f32 v152, v209, v210
	v_cvt_pk_bf16_f32 v153, v211, v212
	v_cvt_pk_bf16_f32 v154, v213, v214
	v_mfma_f32_32x32x16_bf16 v[82:97], v[134:137], v[130:133], v[82:97]
	v_cvt_pk_bf16_f32 v155, v215, v216
	v_cvt_pk_bf16_f32 v156, v217, v218
	v_cvt_pk_bf16_f32 v157, v219, v220
	v_cvt_pk_bf16_f32 v158, v158, v159
	s_waitcnt lgkmcnt(3)
	v_mfma_f32_32x32x16_bf16 v[66:81], v[138:141], v[130:133], v[66:81]
	v_cvt_pk_bf16_f32 v159, v160, v161
	v_cvt_pk_bf16_f32 v160, v162, v163
	v_cvt_pk_bf16_f32 v161, v164, v165
	v_mfma_f32_32x32x16_bf16 v[82:97], v[146:149], v[142:145], v[82:97]
	v_cvt_pk_bf16_f32 v162, v188, v192
	v_cvt_pk_bf16_f32 v163, v193, v194
	v_cvt_pk_bf16_f32 v164, v195, v196
	v_cvt_pk_bf16_f32 v165, v197, v185
	v_mfma_f32_32x32x16_bf16 v[66:81], v[222:225], v[142:145], v[66:81]
	s_nop 1
	v_permlane32_swap_b32_e32 v190, v191
	v_permlane32_swap_b32_e32 v150, v152
	v_permlane32_swap_b32_e32 v151, v153
	s_waitcnt lgkmcnt(0)
	v_mfma_f32_32x32x16_bf16 v[82:97], v[230:233], v[226:229], v[82:97]
	v_permlane32_swap_b32_e32 v154, v156
	v_permlane32_swap_b32_e32 v155, v157
	v_permlane32_swap_b32_e32 v158, v160
	v_mfma_f32_32x32x16_bf16 v[66:81], v[234:237], v[226:229], v[66:81]
	v_permlane32_swap_b32_e32 v159, v161
	v_permlane32_swap_b32_e32 v162, v164
	v_permlane32_swap_b32_e32 v163, v165
	s_add_i32 s75, s75, 2
	s_cmp_le_u32 s75, s87
	s_cselect_b64 s[4:5], -1, 0
	s_cmp_gt_u32 s75, s87
	s_cbranch_scc1 .LBB0_514
	v_add_u32_e32 v146, 0x20000, v254
	global_load_dwordx4 v[130:133], v254, s[98:99] offset:256
	global_load_dwordx4 v[138:141], v254, s[98:99]
	global_load_dwordx4 v[134:137], v146, s[98:99] offset:256
	global_load_dwordx4 v[142:145], v146, s[98:99]
	v_lshlrev_b32_e32 v146, 4, v166
	global_load_dwordx4 v[146:149], v146, s[100:101]
	s_add_u32 s98, s98, 0x40000
	s_addc_u32 s99, s99, 0
	s_add_u32 s100, s100, 0x2000
	s_addc_u32 s101, s101, 0
; __device__ __forceinline__ void partialSM(f32x16& p0, f32x16& p1, float& m_reg, float& mn, float& alpha) {
;     float pmax = p0[0];
; #pragma unroll
;     for (int r = 1; r < 16; ++r) pmax = fmaxf(pmax, p0[r]);
; #pragma unroll
;     for (int r = 0; r < 16; ++r) pmax = fmaxf(pmax, p1[r]);
;     { auto rr = __builtin_amdgcn_permlane32_swap(__float_as_uint(pmax), __float_as_uint(pmax), false, false);
;       pmax = fmaxf(__uint_as_float(rr[0]), __uint_as_float(rr[1])); }
;     constexpr float C2 = 1.4426950408889634f * ATT_SCALE;
;     if (__builtin_expect(__all((pmax - m_reg) * ATT_SCALE <= THR), 1)) { mn = m_reg; alpha = 1.f; }
;     else { mn = fmaxf(m_reg, pmax); alpha = __builtin_amdgcn_exp2f((m_reg - mn) * C2); m_reg = mn; }
;     const float mnL = -mn * C2;
; #pragma unroll
;     for (int r = 0; r < 16; ++r) p0[r] = fmaf(p0[r], C2, mnL);
; #pragma unroll
;     for (int r = 0; r < 16; ++r) p1[r] = fmaf(p1[r], C2, mnL);
; #pragma unroll
;     for (int r = 0; r < 16; ++r) p0[r] = __builtin_amdgcn_exp2f(p0[r]);
; }
; template <int VB>
; __device__ __forceinline__ void pv_tile(f32x16* o, int vb0, bf16x8 pa0, bf16x8 pa1, bf16x8 pa2, bf16x8 pa3) {
;     ...
;     PV_D0(0); PV_D0(1); PV_D0(2); PV_D0(3);
;     ...
; }
.LBB0_514:
	s_sub_i32 s10, s96, 33
	s_cmp_le_i32 s10, s85
	s_cbranch_scc0 .Lattn_slow2
	s_add_i32 s10, s74, 1
	s_cmp_lg_u32 s74, 2
	s_cselect_b32 s74, s10, 0
	s_lshl_b32 s78, s74, 14
	v_add_u32_e32 v242, s78, v169
	ds_read_b64_tr_b16 v[222:223], v242 offset:0
	ds_read_b64_tr_b16 v[224:225], v242 offset:0x800
	ds_read_b64_tr_b16 v[226:227], v242 offset:0x1000
	ds_read_b64_tr_b16 v[228:229], v242 offset:0x1800
	ds_read_b64_tr_b16 v[230:231], v242 offset:0x2000
	ds_read_b64_tr_b16 v[232:233], v242 offset:0x2800
	ds_read_b64_tr_b16 v[234:235], v242 offset:0x3000
	ds_read_b64_tr_b16 v[236:237], v242 offset:0x3800
	v_max_f32_e32 v243, v82, v83
	v_max3_f32 v243, v243, v84, v85
	v_max3_f32 v243, v243, v86, v87
	v_max3_f32 v243, v243, v88, v89
	s_waitcnt lgkmcnt(0)
	s_nop 0
	v_mfma_f32_32x32x16_bf16 v[50:65], v[150:153], v[222:225], v[50:65]
	ds_read_b64_tr_b16 v[222:223], v242 offset:0x200
	ds_read_b64_tr_b16 v[224:225], v242 offset:0xa00
	v_max3_f32 v243, v243, v90, v91
	v_max3_f32 v243, v243, v92, v93
	v_max3_f32 v243, v243, v94, v95
	v_max3_f32 v243, v243, v96, v97
	v_max3_f32 v243, v243, v66, v67
	v_mfma_f32_32x32x16_bf16 v[50:65], v[154:157], v[226:229], v[50:65]
	ds_read_b64_tr_b16 v[226:227], v242 offset:0x1200
	ds_read_b64_tr_b16 v[228:229], v242 offset:0x1a00
	v_max3_f32 v243, v243, v68, v69
	v_max3_f32 v243, v243, v70, v71
	v_max3_f32 v243, v243, v72, v73
	v_max3_f32 v243, v243, v74, v75
	v_max3_f32 v243, v243, v76, v77
	v_max3_f32 v243, v243, v78, v79
	v_mfma_f32_32x32x16_bf16 v[50:65], v[158:161], v[230:233], v[50:65]
	ds_read_b64_tr_b16 v[230:231], v242 offset:0x2200
	ds_read_b64_tr_b16 v[232:233], v242 offset:0x2a00
	ds_read_b64_tr_b16 v[238:239], v242 offset:0x3200
	ds_read_b64_tr_b16 v[240:241], v242 offset:0x3a00
	v_max3_f32 v243, v243, v80, v81
	v_mov_b32_e32 v244, v243
	s_nop 1
	v_permlane32_swap_b32_e32 v243, v244
	v_max_f32_e32 v243, v243, v244
	v_sub_f32_e32 v244, v243, v0
	s_waitcnt lgkmcnt(0)
	v_mfma_f32_32x32x16_bf16 v[50:65], v[162:165], v[234:237], v[50:65]
	v_mul_f32_e32 v244, 0x3d93cd3a, v244
	v_cmp_ge_f32_e32 vcc, s73, v244
	s_cmp_eq_u64 vcc, exec
	s_cselect_b64 s[10:11], -1, 0
	v_max_f32_e32 v245, v0, v243
	v_sub_f32_e32 v246, v0, v245
	v_mfma_f32_32x32x16_bf16 v[34:49], v[150:153], v[222:225], v[34:49]
	ds_read_b64_tr_b16 v[222:223], v242 offset:0x400
	ds_read_b64_tr_b16 v[224:225], v242 offset:0xc00
	v_mul_f32_e32 v246, 0x3dd53b94, v246
	v_exp_f32_e32 v246, v246
	s_nop 0
	v_cndmask_b32_e64 v188, v246, 1.0, s[10:11]
	v_cndmask_b32_e64 v185, v245, v0, s[10:11]
	v_mfma_f32_32x32x16_bf16 v[34:49], v[154:157], v[226:229], v[34:49]
	ds_read_b64_tr_b16 v[226:227], v242 offset:0x1400
	ds_read_b64_tr_b16 v[228:229], v242 offset:0x1c00
	v_mul_f32_e32 v0, 0xbdd53b94, v185
	v_fmamk_f32 v82, v82, 0x3dd53b94, v0
	v_fmamk_f32 v83, v83, 0x3dd53b94, v0
	v_fmamk_f32 v84, v84, 0x3dd53b94, v0
	v_fmamk_f32 v85, v85, 0x3dd53b94, v0
	v_mfma_f32_32x32x16_bf16 v[34:49], v[158:161], v[230:233], v[34:49]
	ds_read_b64_tr_b16 v[230:231], v242 offset:0x2400
	ds_read_b64_tr_b16 v[232:233], v242 offset:0x2c00
	ds_read_b64_tr_b16 v[234:235], v242 offset:0x3400
	ds_read_b64_tr_b16 v[236:237], v242 offset:0x3c00
	v_fmamk_f32 v86, v86, 0x3dd53b94, v0
	v_fmamk_f32 v87, v87, 0x3dd53b94, v0
	v_fmamk_f32 v88, v88, 0x3dd53b94, v0
	v_fmamk_f32 v89, v89, 0x3dd53b94, v0
	v_fmamk_f32 v90, v90, 0x3dd53b94, v0
	v_fmamk_f32 v91, v91, 0x3dd53b94, v0
	s_waitcnt lgkmcnt(0)
	v_mfma_f32_32x32x16_bf16 v[34:49], v[162:165], v[238:241], v[34:49]
	v_fmamk_f32 v92, v92, 0x3dd53b94, v0
	v_fmamk_f32 v93, v93, 0x3dd53b94, v0
	v_fmamk_f32 v94, v94, 0x3dd53b94, v0
	v_fmamk_f32 v95, v95, 0x3dd53b94, v0
	v_fmamk_f32 v96, v96, 0x3dd53b94, v0
	v_mfma_f32_32x32x16_bf16 v[18:33], v[150:153], v[222:225], v[18:33]
	ds_read_b64_tr_b16 v[222:223], v242 offset:0x600
	ds_read_b64_tr_b16 v[224:225], v242 offset:0xe00
	v_fmamk_f32 v97, v97, 0x3dd53b94, v0
	v_exp_f32_e32 v205, v82
	v_exp_f32_e32 v207, v83
	v_exp_f32_e32 v203, v84
	v_mfma_f32_32x32x16_bf16 v[18:33], v[154:157], v[226:229], v[18:33]
	ds_read_b64_tr_b16 v[226:227], v242 offset:0x1600
	ds_read_b64_tr_b16 v[228:229], v242 offset:0x1e00
	v_exp_f32_e32 v206, v85
	v_exp_f32_e32 v202, v86
	v_mfma_f32_32x32x16_bf16 v[18:33], v[158:161], v[230:233], v[18:33]
	ds_read_b64_tr_b16 v[230:231], v242 offset:0x2600
	ds_read_b64_tr_b16 v[232:233], v242 offset:0x2e00
	ds_read_b64_tr_b16 v[238:239], v242 offset:0x3600
	ds_read_b64_tr_b16 v[240:241], v242 offset:0x3e00
	v_exp_f32_e32 v204, v87
	v_exp_f32_e32 v200, v88
	v_exp_f32_e32 v201, v89
	s_waitcnt lgkmcnt(0)
	v_mfma_f32_32x32x16_bf16 v[18:33], v[162:165], v[234:237], v[18:33]
	v_exp_f32_e32 v197, v90
	v_exp_f32_e32 v199, v91
	v_exp_f32_e32 v196, v92
	v_mfma_f32_32x32x16_bf16 v[2:17], v[150:153], v[222:225], v[2:17]
	v_pk_fma_f32 v[152:153], v[78:79], s[80:81], v[0:1] op_sel_hi:[1,0,0]
	v_pk_fma_f32 v[150:151], v[80:81], s[80:81], v[0:1] op_sel_hi:[1,0,0]
	v_exp_f32_e32 v198, v93
	v_exp_f32_e32 v193, v94
	v_exp_f32_e32 v195, v95
	v_mfma_f32_32x32x16_bf16 v[2:17], v[154:157], v[226:229], v[2:17]
	v_pk_fma_f32 v[156:157], v[74:75], s[80:81], v[0:1] op_sel_hi:[1,0,0]
	v_pk_fma_f32 v[154:155], v[76:77], s[80:81], v[0:1] op_sel_hi:[1,0,0]
	v_exp_f32_e32 v192, v96
	v_exp_f32_e32 v194, v97
	v_mfma_f32_32x32x16_bf16 v[2:17], v[158:161], v[230:233], v[2:17]
	v_pk_fma_f32 v[160:161], v[70:71], s[80:81], v[0:1] op_sel_hi:[1,0,0]
	v_pk_fma_f32 v[158:159], v[72:73], s[80:81], v[0:1] op_sel_hi:[1,0,0]
	v_add_f32_e32 v247, v186, v187
	v_fmac_f32_e32 v247, v183, v181
	v_add_f32_e32 v181, v190, v191
	v_fmac_f32_e32 v181, v247, v189
	v_add_u32_e32 v184, 0xffffff80, v184
	v_mfma_f32_32x32x16_bf16 v[2:17], v[162:165], v[238:241], v[2:17]
	s_setprio 0
	v_pk_fma_f32 v[164:165], v[66:67], s[80:81], v[0:1] op_sel_hi:[1,0,0]
	v_pk_fma_f32 v[162:163], v[68:69], s[80:81], v[0:1] op_sel_hi:[1,0,0]
	s_andn2_b64 vcc, exec, s[4:5]
	s_cbranch_vccnz .Lattn_f2_nostage
	s_waitcnt vmcnt(3)
	v_add_u32_e32 v243, s77, v250
	ds_write_b128 v243, v[138:141]
	s_waitcnt vmcnt(1)
	ds_write_b128 v243, v[142:145] offset:8704
	s_waitcnt vmcnt(0)
	v_add_u32_e32 v244, s72, v251
	ds_write_b128 v244, v[146:149]
	s_addk_i32 s78, 0xc000
	s_cmp_lg_u32 s74, 0
	s_cselect_b32 s4, s78, 0x8000
	v_add_u32_e32 v245, s4, v252
	v_add_u32_e32 v246, s4, v253
	ds_write_b128 v245, v[130:133]
	ds_write_b128 v246, v[134:137]

; __device__ __forceinline__ void mask_tile(f32x16& p0, f32x16& p1, int dq) {
;     const float NEG = -__builtin_inff();
; #pragma unroll
;     for (int r = 0; r < 16; ++r) { const int c = (r & 3) + 8 * (r >> 2); if (dq - c < 0) p0[r] = NEG; if (dq - c - 32 < 0) p1[r] = NEG; }
; }
; template <int VB>
; __device__ __forceinline__ void pv_tile(f32x16* o, int vb0, bf16x8 pa0, bf16x8 pa1, bf16x8 pa2, bf16x8 pa3) {
;     ...
;     PV_D0(0); PV_D0(1); PV_D0(2); PV_D0(3);
;     ...
; }
.Lattn_slow2:
	s_add_i32 s10, s74, 1
	s_cmp_lg_u32 s74, 2
	s_cselect_b32 s74, s10, 0
	s_lshl_b32 s78, s74, 14
	v_add_u32_e32 v185, s78, v169
	ds_read_b64_tr_b16 v[192:193], v185 offset:0
	ds_read_b64_tr_b16 v[194:195], v185 offset:0x800
	ds_read_b64_tr_b16 v[196:197], v185 offset:0x1000
	ds_read_b64_tr_b16 v[198:199], v185 offset:0x1800
	ds_read_b64_tr_b16 v[200:201], v185 offset:0x2000
	ds_read_b64_tr_b16 v[202:203], v185 offset:0x2800
	ds_read_b64_tr_b16 v[204:205], v185 offset:0x3000
	ds_read_b64_tr_b16 v[206:207], v185 offset:0x3800
	s_waitcnt lgkmcnt(0)
	s_nop 0
	v_mfma_f32_32x32x16_bf16 v[50:65], v[150:153], v[192:195], v[50:65]
	ds_read_b64_tr_b16 v[192:193], v185 offset:0x200
	ds_read_b64_tr_b16 v[194:195], v185 offset:0xa00
	v_mfma_f32_32x32x16_bf16 v[50:65], v[154:157], v[196:199], v[50:65]
	ds_read_b64_tr_b16 v[196:197], v185 offset:0x1200
	ds_read_b64_tr_b16 v[198:199], v185 offset:0x1a00
	v_mfma_f32_32x32x16_bf16 v[50:65], v[158:161], v[200:203], v[50:65]
	ds_read_b64_tr_b16 v[200:201], v185 offset:0x2200
	ds_read_b64_tr_b16 v[202:203], v185 offset:0x2a00
	ds_read_b64_tr_b16 v[210:211], v185 offset:0x3200
	ds_read_b64_tr_b16 v[212:213], v185 offset:0x3a00
	s_waitcnt lgkmcnt(0)
	v_mfma_f32_32x32x16_bf16 v[50:65], v[162:165], v[204:207], v[50:65]
	v_mfma_f32_32x32x16_bf16 v[34:49], v[150:153], v[192:195], v[34:49]
	ds_read_b64_tr_b16 v[192:193], v185 offset:0x400
	ds_read_b64_tr_b16 v[194:195], v185 offset:0xc00
	v_mfma_f32_32x32x16_bf16 v[34:49], v[154:157], v[196:199], v[34:49]
	ds_read_b64_tr_b16 v[196:197], v185 offset:0x1400
	ds_read_b64_tr_b16 v[198:199], v185 offset:0x1c00
	v_mfma_f32_32x32x16_bf16 v[34:49], v[158:161], v[200:203], v[34:49]
	ds_read_b64_tr_b16 v[200:201], v185 offset:0x2400
	ds_read_b64_tr_b16 v[202:203], v185 offset:0x2c00
	ds_read_b64_tr_b16 v[204:205], v185 offset:0x3400
	ds_read_b64_tr_b16 v[206:207], v185 offset:0x3c00
	s_waitcnt lgkmcnt(0)
	v_mfma_f32_32x32x16_bf16 v[34:49], v[162:165], v[210:213], v[34:49]
	v_mfma_f32_32x32x16_bf16 v[18:33], v[150:153], v[192:195], v[18:33]
	ds_read_b64_tr_b16 v[192:193], v185 offset:0x600
	ds_read_b64_tr_b16 v[194:195], v185 offset:0xe00
	v_mfma_f32_32x32x16_bf16 v[18:33], v[154:157], v[196:199], v[18:33]
	ds_read_b64_tr_b16 v[196:197], v185 offset:0x1600
	ds_read_b64_tr_b16 v[198:199], v185 offset:0x1e00
	v_mfma_f32_32x32x16_bf16 v[18:33], v[158:161], v[200:203], v[18:33]
	ds_read_b64_tr_b16 v[200:201], v185 offset:0x2600
	ds_read_b64_tr_b16 v[202:203], v185 offset:0x2e00
	ds_read_b64_tr_b16 v[210:211], v185 offset:0x3600
	ds_read_b64_tr_b16 v[212:213], v185 offset:0x3e00
	s_waitcnt lgkmcnt(0)
	v_mfma_f32_32x32x16_bf16 v[18:33], v[162:165], v[204:207], v[18:33]
	v_mfma_f32_32x32x16_bf16 v[2:17], v[150:153], v[192:195], v[2:17]
	s_sub_i32 s10, s96, 33
	s_cmp_le_i32 s10, s85
	v_mfma_f32_32x32x16_bf16 v[2:17], v[154:157], v[196:199], v[2:17]
	v_mfma_f32_32x32x16_bf16 v[2:17], v[158:161], v[200:203], v[2:17]
	v_mfma_f32_32x32x16_bf16 v[2:17], v[162:165], v[210:213], v[2:17]
	s_setprio 0
	s_cbranch_scc1 .LBB0_516
	v_subrev_u32_e32 v150, 64, v184
	v_cmp_gt_i32_e64 s[68:69], 26, v150
	v_cmp_gt_i32_e64 s[70:71], 27, v150
	v_cmp_gt_i32_e64 s[66:67], 25, v150
	s_and_b64 s[68:69], s[70:71], s[68:69]
	v_cmp_gt_i32_e64 s[64:65], 24, v150
	s_and_b64 s[66:67], s[68:69], s[66:67]
	v_cmp_gt_i32_e64 s[62:63], 19, v150
	s_and_b64 s[64:65], s[66:67], s[64:65]
	v_cmp_gt_i32_e64 s[60:61], 18, v150
	s_and_b64 s[62:63], s[64:65], s[62:63]
	v_cmp_gt_i32_e64 s[58:59], 17, v150
	s_and_b64 s[60:61], s[62:63], s[60:61]
	v_cmp_gt_i32_e64 s[56:57], 16, v150
	s_and_b64 s[58:59], s[60:61], s[58:59]
	v_cmp_gt_i32_e64 s[54:55], 11, v150
	s_and_b64 s[56:57], s[58:59], s[56:57]
	v_cmp_gt_i32_e64 s[52:53], 10, v150
	s_and_b64 s[54:55], s[56:57], s[54:55]
	v_cmp_gt_i32_e64 s[50:51], 9, v150
	s_and_b64 s[52:53], s[54:55], s[52:53]
	v_cmp_gt_i32_e64 s[48:49], 8, v150
	s_and_b64 s[50:51], s[52:53], s[50:51]
	v_cmp_gt_i32_e64 s[46:47], 3, v150
	s_and_b64 s[48:49], s[50:51], s[48:49]
	v_cmp_gt_i32_e64 s[44:45], 2, v150
	s_and_b64 s[46:47], s[48:49], s[46:47]
	v_cmp_gt_i32_e64 s[42:43], 1, v150
	s_and_b64 s[44:45], s[46:47], s[44:45]
	v_cmp_gt_i32_e64 s[40:41], 0, v150
	s_and_b64 s[42:43], s[44:45], s[42:43]
	s_and_b64 s[40:41], s[42:43], s[40:41]
	v_cmp_gt_i32_e64 s[38:39], 58, v150
	v_cndmask_b32_e64 v82, v82, v174, s[40:41]
	v_cmp_gt_i32_e64 s[40:41], 59, v150
	v_cmp_gt_i32_e64 s[36:37], 57, v150
	s_and_b64 s[38:39], s[40:41], s[38:39]
	v_cmp_gt_i32_e64 s[34:35], 56, v150
	s_and_b64 s[36:37], s[38:39], s[36:37]
	v_cmp_gt_i32_e64 s[30:31], 51, v150
	s_and_b64 s[34:35], s[36:37], s[34:35]
	v_cmp_gt_i32_e64 s[28:29], 50, v150
	s_and_b64 s[30:31], s[34:35], s[30:31]
	v_cmp_gt_i32_e64 s[26:27], 49, v150
	s_and_b64 s[28:29], s[30:31], s[28:29]
	v_cmp_gt_i32_e64 s[24:25], 48, v150
	s_and_b64 s[26:27], s[28:29], s[26:27]
	v_cmp_gt_i32_e64 s[22:23], 43, v150
	s_and_b64 s[24:25], s[26:27], s[24:25]
	v_cmp_gt_i32_e64 s[20:21], 42, v150
	s_and_b64 s[22:23], s[24:25], s[22:23]
	v_cmp_gt_i32_e64 s[18:19], 41, v150
	s_and_b64 s[20:21], s[22:23], s[20:21]
	v_cmp_gt_i32_e64 s[16:17], 40, v150
	s_and_b64 s[18:19], s[20:21], s[18:19]
	v_cmp_gt_i32_e64 s[14:15], 35, v150
	s_and_b64 s[16:17], s[18:19], s[16:17]
	v_cmp_gt_i32_e64 s[12:13], 34, v150
	s_and_b64 s[14:15], s[16:17], s[14:15]
	v_cmp_gt_i32_e64 s[10:11], 33, v150
	s_and_b64 s[12:13], s[14:15], s[12:13]
	v_cmp_gt_i32_e32 vcc, 32, v150
	s_and_b64 s[10:11], s[12:13], s[10:11]
	s_and_b64 vcc, s[10:11], vcc
	v_cndmask_b32_e64 v97, v97, v174, s[70:71]
	v_cndmask_b32_e64 v96, v96, v174, s[68:69]
	v_cndmask_b32_e64 v95, v95, v174, s[66:67]
	v_cndmask_b32_e64 v94, v94, v174, s[64:65]
	v_cndmask_b32_e64 v93, v93, v174, s[62:63]
	v_cndmask_b32_e64 v92, v92, v174, s[60:61]
	v_cndmask_b32_e64 v91, v91, v174, s[58:59]
	v_cndmask_b32_e64 v90, v90, v174, s[56:57]
	v_cndmask_b32_e64 v89, v89, v174, s[54:55]
	v_cndmask_b32_e64 v88, v88, v174, s[52:53]
	v_cndmask_b32_e64 v87, v87, v174, s[50:51]
	v_cndmask_b32_e64 v86, v86, v174, s[48:49]
	v_cndmask_b32_e64 v85, v85, v174, s[46:47]
	v_cndmask_b32_e64 v84, v84, v174, s[44:45]
	v_cndmask_b32_e64 v83, v83, v174, s[42:43]
	v_cndmask_b32_e64 v81, v81, v174, s[40:41]
	v_cndmask_b32_e64 v80, v80, v174, s[38:39]
	v_cndmask_b32_e64 v79, v79, v174, s[36:37]
	v_cndmask_b32_e64 v78, v78, v174, s[34:35]
	v_cndmask_b32_e64 v77, v77, v174, s[30:31]
	v_cndmask_b32_e64 v76, v76, v174, s[28:29]
	v_cndmask_b32_e64 v75, v75, v174, s[26:27]
	v_cndmask_b32_e64 v74, v74, v174, s[24:25]
	v_cndmask_b32_e64 v73, v73, v174, s[22:23]
	v_cndmask_b32_e64 v72, v72, v174, s[20:21]
	v_cndmask_b32_e64 v71, v71, v174, s[18:19]
	v_cndmask_b32_e64 v70, v70, v174, s[16:17]
	v_cndmask_b32_e64 v69, v69, v174, s[14:15]
	v_cndmask_b32_e64 v68, v68, v174, s[12:13]
	v_cndmask_b32_e64 v67, v67, v174, s[10:11]
	v_cndmask_b32_e32 v66, v66, v174, vcc

; __device__ __forceinline__ void mask_tile(f32x16& p0, f32x16& p1, int dq) {
;     const float NEG = -__builtin_inff();
; #pragma unroll
;     for (int r = 0; r < 16; ++r) { const int c = (r & 3) + 8 * (r >> 2); if (dq - c < 0) p0[r] = NEG; if (dq - c - 32 < 0) p1[r] = NEG; }
; }
; template <int VB>
; __device__ __forceinline__ void pv_tile(f32x16* o, int vb0, bf16x8 pa0, bf16x8 pa1, bf16x8 pa2, bf16x8 pa3) {
;     ...
;     PV_D0(0); PV_D0(1); PV_D0(2); PV_D0(3);
;     ...
; }
.Lattn_slow1:
	s_lshl_b32 s4, s74, 14
	v_add_u32_e32 v0, s4, v169
	ds_read_b64_tr_b16 v[188:189], v0 offset:0
	ds_read_b64_tr_b16 v[190:191], v0 offset:0x800
	ds_read_b64_tr_b16 v[192:193], v0 offset:0x1000
	ds_read_b64_tr_b16 v[194:195], v0 offset:0x1800
	ds_read_b64_tr_b16 v[196:197], v0 offset:0x2000
	ds_read_b64_tr_b16 v[198:199], v0 offset:0x2800
	ds_read_b64_tr_b16 v[200:201], v0 offset:0x3000
	ds_read_b64_tr_b16 v[202:203], v0 offset:0x3800
	s_waitcnt lgkmcnt(0)
	s_nop 0
	v_mfma_f32_32x32x16_bf16 v[50:65], v[150:153], v[188:191], v[50:65]
	ds_read_b64_tr_b16 v[188:189], v0 offset:0x200
	ds_read_b64_tr_b16 v[190:191], v0 offset:0xa00
	v_mfma_f32_32x32x16_bf16 v[50:65], v[154:157], v[192:195], v[50:65]
	ds_read_b64_tr_b16 v[192:193], v0 offset:0x1200
	ds_read_b64_tr_b16 v[194:195], v0 offset:0x1a00
	v_mfma_f32_32x32x16_bf16 v[50:65], v[158:161], v[196:199], v[50:65]
	ds_read_b64_tr_b16 v[196:197], v0 offset:0x2200
	ds_read_b64_tr_b16 v[198:199], v0 offset:0x2a00
	ds_read_b64_tr_b16 v[204:205], v0 offset:0x3200
	ds_read_b64_tr_b16 v[206:207], v0 offset:0x3a00
	s_waitcnt lgkmcnt(0)
	v_mfma_f32_32x32x16_bf16 v[50:65], v[162:165], v[200:203], v[50:65]
	v_mfma_f32_32x32x16_bf16 v[34:49], v[150:153], v[188:191], v[34:49]
	ds_read_b64_tr_b16 v[188:189], v0 offset:0x400
	ds_read_b64_tr_b16 v[190:191], v0 offset:0xc00
	v_mfma_f32_32x32x16_bf16 v[34:49], v[154:157], v[192:195], v[34:49]
	ds_read_b64_tr_b16 v[192:193], v0 offset:0x1400
	ds_read_b64_tr_b16 v[194:195], v0 offset:0x1c00
	v_mfma_f32_32x32x16_bf16 v[34:49], v[158:161], v[196:199], v[34:49]
	ds_read_b64_tr_b16 v[196:197], v0 offset:0x2400
	ds_read_b64_tr_b16 v[198:199], v0 offset:0x2c00
	ds_read_b64_tr_b16 v[200:201], v0 offset:0x3400
	ds_read_b64_tr_b16 v[202:203], v0 offset:0x3c00
	s_waitcnt lgkmcnt(0)
	v_mfma_f32_32x32x16_bf16 v[34:49], v[162:165], v[204:207], v[34:49]
	v_mfma_f32_32x32x16_bf16 v[18:33], v[150:153], v[188:191], v[18:33]
	ds_read_b64_tr_b16 v[188:189], v0 offset:0x600
	ds_read_b64_tr_b16 v[190:191], v0 offset:0xe00
	v_mfma_f32_32x32x16_bf16 v[18:33], v[154:157], v[192:195], v[18:33]
	ds_read_b64_tr_b16 v[192:193], v0 offset:0x1600
	ds_read_b64_tr_b16 v[194:195], v0 offset:0x1e00
	v_mfma_f32_32x32x16_bf16 v[18:33], v[158:161], v[196:199], v[18:33]
	ds_read_b64_tr_b16 v[196:197], v0 offset:0x2600
	ds_read_b64_tr_b16 v[198:199], v0 offset:0x2e00
	ds_read_b64_tr_b16 v[204:205], v0 offset:0x3600
	ds_read_b64_tr_b16 v[206:207], v0 offset:0x3e00
	s_waitcnt lgkmcnt(0)
	v_mfma_f32_32x32x16_bf16 v[18:33], v[162:165], v[200:203], v[18:33]
	v_mfma_f32_32x32x16_bf16 v[2:17], v[150:153], v[188:191], v[2:17]
	s_add_i32 s5, s96, 0xffffff9f
	s_cmp_le_i32 s5, s85
	v_mfma_f32_32x32x16_bf16 v[2:17], v[154:157], v[192:195], v[2:17]
	v_mfma_f32_32x32x16_bf16 v[2:17], v[158:161], v[196:199], v[2:17]
	v_mfma_f32_32x32x16_bf16 v[2:17], v[162:165], v[204:207], v[2:17]
	s_setprio 0
	s_cbranch_scc1 .LBB0_508
	v_cmp_gt_i32_e64 s[68:69], 26, v184
	v_cmp_gt_i32_e64 s[70:71], 27, v184
	v_cmp_gt_i32_e64 s[66:67], 25, v184
	s_and_b64 s[68:69], s[70:71], s[68:69]
	v_cmp_gt_i32_e64 s[64:65], 24, v184
	s_and_b64 s[66:67], s[68:69], s[66:67]
	v_cmp_gt_i32_e64 s[62:63], 19, v184
	s_and_b64 s[64:65], s[66:67], s[64:65]
	v_cmp_gt_i32_e64 s[60:61], 18, v184
	s_and_b64 s[62:63], s[64:65], s[62:63]
	v_cmp_gt_i32_e64 s[58:59], 17, v184
	s_and_b64 s[60:61], s[62:63], s[60:61]
	v_cmp_gt_i32_e64 s[56:57], 16, v184
	s_and_b64 s[58:59], s[60:61], s[58:59]
	v_cmp_gt_i32_e64 s[54:55], 11, v184
	s_and_b64 s[56:57], s[58:59], s[56:57]
	v_cmp_gt_i32_e64 s[52:53], 10, v184
	s_and_b64 s[54:55], s[56:57], s[54:55]
	v_cmp_gt_i32_e64 s[50:51], 9, v184
	s_and_b64 s[52:53], s[54:55], s[52:53]
	v_cmp_gt_i32_e64 s[48:49], 8, v184
	s_and_b64 s[50:51], s[52:53], s[50:51]
	v_cmp_gt_i32_e64 s[46:47], 3, v184
	s_and_b64 s[48:49], s[50:51], s[48:49]
	v_cmp_gt_i32_e64 s[44:45], 2, v184
	s_and_b64 s[46:47], s[48:49], s[46:47]
	v_cmp_gt_i32_e64 s[42:43], 1, v184
	s_and_b64 s[44:45], s[46:47], s[44:45]
	v_cmp_gt_i32_e64 s[40:41], 0, v184
	s_and_b64 s[42:43], s[44:45], s[42:43]
	s_and_b64 s[40:41], s[42:43], s[40:41]
	v_cmp_gt_i32_e64 s[38:39], 58, v184
	v_cndmask_b32_e64 v82, v82, v174, s[40:41]
	v_cmp_gt_i32_e64 s[40:41], 59, v184
	v_cmp_gt_i32_e64 s[36:37], 57, v184
	s_and_b64 s[38:39], s[40:41], s[38:39]
	v_cmp_gt_i32_e64 s[34:35], 56, v184
	s_and_b64 s[36:37], s[38:39], s[36:37]
	v_cmp_gt_i32_e64 s[30:31], 51, v184
	s_and_b64 s[34:35], s[36:37], s[34:35]
	v_cmp_gt_i32_e64 s[28:29], 50, v184
	s_and_b64 s[30:31], s[34:35], s[30:31]
	v_cmp_gt_i32_e64 s[26:27], 49, v184
	s_and_b64 s[28:29], s[30:31], s[28:29]
	v_cmp_gt_i32_e64 s[24:25], 48, v184
	s_and_b64 s[26:27], s[28:29], s[26:27]
	v_cmp_gt_i32_e64 s[22:23], 43, v184
	s_and_b64 s[24:25], s[26:27], s[24:25]
	v_cmp_gt_i32_e64 s[20:21], 42, v184
	s_and_b64 s[22:23], s[24:25], s[22:23]
	v_cmp_gt_i32_e64 s[18:19], 41, v184
	s_and_b64 s[20:21], s[22:23], s[20:21]
	v_cmp_gt_i32_e64 s[16:17], 40, v184
	s_and_b64 s[18:19], s[20:21], s[18:19]
	v_cmp_gt_i32_e64 s[14:15], 35, v184
	s_and_b64 s[16:17], s[18:19], s[16:17]
	v_cmp_gt_i32_e64 s[12:13], 34, v184
	s_and_b64 s[14:15], s[16:17], s[14:15]
	v_cmp_gt_i32_e64 s[10:11], 33, v184
	s_and_b64 s[12:13], s[14:15], s[12:13]
	v_cmp_gt_i32_e32 vcc, 32, v184
	s_and_b64 s[10:11], s[12:13], s[10:11]
	s_and_b64 vcc, s[10:11], vcc
	v_cndmask_b32_e64 v97, v97, v174, s[70:71]
	v_cndmask_b32_e64 v96, v96, v174, s[68:69]
	v_cndmask_b32_e64 v95, v95, v174, s[66:67]
	v_cndmask_b32_e64 v94, v94, v174, s[64:65]
	v_cndmask_b32_e64 v93, v93, v174, s[62:63]
	v_cndmask_b32_e64 v92, v92, v174, s[60:61]
	v_cndmask_b32_e64 v91, v91, v174, s[58:59]
	v_cndmask_b32_e64 v90, v90, v174, s[56:57]
	v_cndmask_b32_e64 v89, v89, v174, s[54:55]
	v_cndmask_b32_e64 v88, v88, v174, s[52:53]
	v_cndmask_b32_e64 v87, v87, v174, s[50:51]
	v_cndmask_b32_e64 v86, v86, v174, s[48:49]
	v_cndmask_b32_e64 v85, v85, v174, s[46:47]
	v_cndmask_b32_e64 v84, v84, v174, s[44:45]
	v_cndmask_b32_e64 v83, v83, v174, s[42:43]
	v_cndmask_b32_e64 v81, v81, v174, s[40:41]
	v_cndmask_b32_e64 v80, v80, v174, s[38:39]
	v_cndmask_b32_e64 v79, v79, v174, s[36:37]
	v_cndmask_b32_e64 v78, v78, v174, s[34:35]
	v_cndmask_b32_e64 v77, v77, v174, s[30:31]
	v_cndmask_b32_e64 v76, v76, v174, s[28:29]
	v_cndmask_b32_e64 v75, v75, v174, s[26:27]
	v_cndmask_b32_e64 v74, v74, v174, s[24:25]
	v_cndmask_b32_e64 v73, v73, v174, s[22:23]
	v_cndmask_b32_e64 v72, v72, v174, s[20:21]
	v_cndmask_b32_e64 v71, v71, v174, s[18:19]
	v_cndmask_b32_e64 v70, v70, v174, s[16:17]
	v_cndmask_b32_e64 v69, v69, v174, s[14:15]
	v_cndmask_b32_e64 v68, v68, v174, s[12:13]
	v_cndmask_b32_e64 v67, v67, v174, s[10:11]
	v_cndmask_b32_e32 v66, v66, v174, vcc
